# P5 GEMM epilogue: load blocks of groups 2 and 6 issued one group ahead (renamed into free VGPRs)
# speedup vs baseline: 1.0016x; 1.0016x over previous
.LBB0_802:
	v_lshl_or_b32 v130, s20, 8, v196
	v_ashrrev_i32_e32 v131, 31, v130
	v_lshlrev_b64 v[152:153], 1, v[130:131]
	v_lshl_add_u32 v160, s33, 8, v194
	v_lshl_add_u64 v[158:159], s[8:9], 0, v[152:153]
	v_mad_i64_i32 v[162:163], s[0:1], v160, s97, v[158:159]
	global_load_dwordx4 v[198:201], v[162:163], off
	v_ashrrev_i32_e32 v161, 31, v160
	v_lshl_add_u64 v[154:155], s[10:11], 0, v[152:153]
	v_lshl_add_u64 v[156:157], s[6:7], 0, v[152:153]
	v_lshlrev_b64 v[182:183], 11, v[160:161]
	v_lshl_add_u64 v[164:165], v[156:157], 0, v[182:183]
	v_lshl_add_u64 v[166:167], v[154:155], 0, v[182:183]
	global_load_dwordx4 v[202:205], v[164:165], off
	global_load_dwordx4 v[206:209], v[166:167], off
	v_or_b32_e32 v130, 16, v160
	v_mad_i64_i32 v[178:179], s[0:1], v130, s97, v[158:159]
	global_load_dwordx4 v[138:141], v[178:179], off
	v_ashrrev_i32_e32 v131, 31, v130
	v_lshlrev_b64 v[180:181], 11, v[130:131]
	v_lshl_add_u64 v[168:169], v[154:155], 0, v[180:181]
	global_load_dwordx4 v[130:133], v[168:169], off
	v_lshl_add_u64 v[176:177], v[156:157], 0, v[180:181]
	global_load_dwordx4 v[134:137], v[176:177], off
	s_and_b64 vcc, exec, s[2:3]
	s_waitcnt vmcnt(0) lgkmcnt(0)
	v_lshlrev_b32_e32 v161, 16, v198
	v_exp_f32_e32 v161, v161
	v_and_b32_e32 v172, 0xffff0000, v198
	v_lshlrev_b32_e32 v173, 16, v199
	v_and_b32_e32 v174, 0xffff0000, v199
	v_add_f32_e32 v161, 1.0, v161
	v_rcp_f32_e32 v161, v161
	v_lshlrev_b32_e32 v175, 16, v200
	v_and_b32_e32 v184, 0xffff0000, v200
	v_lshlrev_b32_e32 v185, 16, v201
	v_and_b32_e32 v186, 0xffff0000, v201
	v_lshlrev_b32_e32 v187, 16, v202
	v_and_b32_e32 v198, 0xffff0000, v202
	v_lshlrev_b32_e32 v199, 16, v203
	v_and_b32_e32 v200, 0xffff0000, v203
	v_lshlrev_b32_e32 v201, 16, v204
	v_and_b32_e32 v202, 0xffff0000, v204
	v_lshlrev_b32_e32 v203, 16, v205
	v_and_b32_e32 v204, 0xffff0000, v205
	v_lshlrev_b32_e32 v205, 16, v206
	v_fmac_f32_e32 v205, v126, v161
	v_exp_f32_e32 v161, v175
	v_lshlrev_b32_e32 v211, 16, v208
	v_and_b32_e32 v206, 0xffff0000, v206
	v_and_b32_e32 v208, 0xffff0000, v208
	v_add_f32_e32 v161, 1.0, v161
	v_rcp_f32_e32 v161, v161
	v_lshlrev_b32_e32 v210, 16, v207
	v_lshlrev_b32_e32 v212, 16, v209
	v_and_b32_e32 v207, 0xffff0000, v207
	v_fmac_f32_e32 v211, v122, v161
	v_exp_f32_e32 v122, v172
	v_and_b32_e32 v209, 0xffff0000, v209
	v_add_f32_e32 v126, v205, v187
	v_add_f32_e32 v161, v211, v201
	v_add_f32_e32 v122, 1.0, v122
	v_rcp_f32_e32 v122, v122
	v_lshlrev_b32_e32 v175, 16, v132
	v_and_b32_e32 v132, 0xffff0000, v132
	v_lshlrev_b32_e32 v172, 16, v137
	v_fmac_f32_e32 v206, v127, v122
	v_exp_f32_e32 v127, v184
	v_add_f32_e32 v122, v206, v198
	v_cvt_pk_bf16_f32 v122, v126, v122
	v_and_b32_e32 v137, 0xffff0000, v137
	v_add_f32_e32 v127, 1.0, v127
	v_rcp_f32_e32 v127, v127
	s_nop 0
	v_fmac_f32_e32 v208, v123, v127
	v_exp_f32_e32 v123, v173
	v_add_f32_e32 v127, v208, v202
	v_lshlrev_b32_e32 v173, 16, v130
	v_and_b32_e32 v130, 0xffff0000, v130
	v_add_f32_e32 v123, 1.0, v123
	v_rcp_f32_e32 v123, v123
	s_nop 0
	v_fmac_f32_e32 v210, v128, v123
	v_exp_f32_e32 v128, v185
	v_add_f32_e32 v123, v210, v199
	v_add_f32_e32 v128, 1.0, v128
	v_rcp_f32_e32 v128, v128
	s_nop 0
	v_fmac_f32_e32 v212, v124, v128
	v_exp_f32_e32 v124, v174
	v_add_f32_e32 v128, v212, v203
	v_lshlrev_b32_e32 v174, 16, v131
	v_and_b32_e32 v131, 0xffff0000, v131
	v_add_f32_e32 v124, 1.0, v124
	v_rcp_f32_e32 v124, v124
	s_nop 0
	v_fmac_f32_e32 v207, v129, v124
	v_exp_f32_e32 v129, v186
	v_add_f32_e32 v124, v207, v200
	v_cvt_pk_bf16_f32 v123, v123, v124
	v_cvt_pk_bf16_f32 v124, v161, v127
	v_add_f32_e32 v129, 1.0, v129
	v_rcp_f32_e32 v129, v129
	v_lshl_add_u64 v[126:127], s[6:7], 0, v[182:183]
	v_lshl_add_u64 v[126:127], v[126:127], 0, v[152:153]
	v_lshlrev_b32_e32 v182, 16, v133
	v_fmac_f32_e32 v209, v125, v129
	v_add_f32_e32 v125, v209, v204
	v_cvt_pk_bf16_f32 v125, v128, v125
	global_store_dwordx4 v[126:127], v[122:125], off
	s_nop 1
	v_lshlrev_b32_e32 v128, 16, v140
	v_and_b32_e32 v129, 0xffff0000, v140
	v_lshlrev_b32_e32 v122, 16, v138
	v_exp_f32_e32 v122, v122
	v_and_b32_e32 v123, 0xffff0000, v138
	v_lshlrev_b32_e32 v124, 16, v139
	v_lshlrev_b32_e32 v138, 16, v141
	v_add_f32_e32 v122, 1.0, v122
	v_rcp_f32_e32 v122, v122
	v_and_b32_e32 v125, 0xffff0000, v139
	v_and_b32_e32 v139, 0xffff0000, v141
	v_lshlrev_b32_e32 v140, 16, v134
	v_fmac_f32_e32 v173, v118, v122
	v_exp_f32_e32 v122, v128
	v_and_b32_e32 v134, 0xffff0000, v134
	v_lshlrev_b32_e32 v141, 16, v135
	v_and_b32_e32 v135, 0xffff0000, v135
	v_add_f32_e32 v122, 1.0, v122
	v_rcp_f32_e32 v122, v122
	v_lshlrev_b32_e32 v161, 16, v136
	v_and_b32_e32 v136, 0xffff0000, v136
	v_and_b32_e32 v133, 0xffff0000, v133
	v_fmac_f32_e32 v175, v114, v122
	v_exp_f32_e32 v114, v123
	v_add_f32_e32 v118, v173, v140
	v_add_f32_e32 v122, v175, v161
	v_add_f32_e32 v114, 1.0, v114
	v_rcp_f32_e32 v114, v114
	s_nop 0
	v_fmac_f32_e32 v130, v119, v114
	v_exp_f32_e32 v119, v129
	v_add_f32_e32 v114, v130, v134
	v_cvt_pk_bf16_f32 v114, v118, v114
	v_add_f32_e32 v119, 1.0, v119
	v_rcp_f32_e32 v119, v119
	s_nop 0
	v_fmac_f32_e32 v132, v115, v119
	v_exp_f32_e32 v115, v124
	v_add_f32_e32 v119, v132, v136
	v_add_f32_e32 v115, 1.0, v115
	v_rcp_f32_e32 v115, v115
	s_nop 0
	v_fmac_f32_e32 v174, v120, v115
	v_exp_f32_e32 v120, v138
	v_add_f32_e32 v115, v174, v141
	v_add_f32_e32 v120, 1.0, v120
	v_rcp_f32_e32 v120, v120
	s_nop 0
	v_fmac_f32_e32 v182, v116, v120
	v_exp_f32_e32 v116, v125
	v_add_f32_e32 v120, v182, v172
	v_add_f32_e32 v116, 1.0, v116
	v_rcp_f32_e32 v116, v116
	s_nop 0
	v_fmac_f32_e32 v131, v121, v116
	v_exp_f32_e32 v121, v139
	v_add_f32_e32 v116, v131, v135
	v_cvt_pk_bf16_f32 v115, v115, v116
	v_cvt_pk_bf16_f32 v116, v122, v119
	v_add_f32_e32 v121, 1.0, v121
	v_rcp_f32_e32 v121, v121
	v_lshl_add_u64 v[118:119], s[6:7], 0, v[180:181]
	v_lshl_add_u64 v[128:129], v[118:119], 0, v[152:153]
	v_fmac_f32_e32 v133, v117, v121
	v_add_f32_e32 v117, v133, v137
	v_cvt_pk_bf16_f32 v117, v120, v117
	global_store_dwordx4 v[128:129], v[114:117], off
	s_nop 1
	v_or_b32_e32 v114, 32, v160
	v_mad_i64_i32 v[130:131], s[0:1], v114, s97, v[158:159]
	global_load_dwordx4 v[198:201], v[130:131], off
	v_ashrrev_i32_e32 v115, 31, v114
	v_lshlrev_b64 v[182:183], 11, v[114:115]
	v_lshl_add_u64 v[132:133], v[156:157], 0, v[182:183]
	v_lshl_add_u64 v[134:135], v[154:155], 0, v[182:183]
	global_load_dwordx4 v[202:205], v[132:133], off
	global_load_dwordx4 v[206:209], v[134:135], off
	v_or_b32_e32 v114, 48, v160
	v_mad_i64_i32 v[136:137], s[0:1], v114, s97, v[158:159]
	global_load_dwordx4 v[122:125], v[136:137], off
	v_ashrrev_i32_e32 v115, 31, v114
	v_lshlrev_b64 v[180:181], 11, v[114:115]
	v_lshl_add_u64 v[138:139], v[156:157], 0, v[180:181]
	v_lshl_add_u64 v[140:141], v[154:155], 0, v[180:181]
	global_load_dwordx4 v[114:117], v[138:139], off
	global_load_dwordx4 v[118:121], v[140:141], off
	s_waitcnt vmcnt(0) lgkmcnt(0)
	global_load_dwordx4 v[190:193], v[162:163], off offset:256
	global_load_dwordx4 v[214:217], v[164:165], off offset:256
	global_load_dwordx4 v[218:221], v[166:167], off offset:256
	global_load_dwordx4 v[222:225], v[178:179], off offset:256
	global_load_dwordx4 v[236:239], v[176:177], off offset:256
	global_load_dwordx4 v[240:243], v[168:169], off offset:256
	v_lshlrev_b32_e32 v161, 16, v198
	v_exp_f32_e32 v161, v161
	v_and_b32_e32 v172, 0xffff0000, v198
	v_lshlrev_b32_e32 v173, 16, v199
	v_and_b32_e32 v174, 0xffff0000, v199
	v_add_f32_e32 v161, 1.0, v161
	v_rcp_f32_e32 v161, v161
	v_lshlrev_b32_e32 v175, 16, v200
	v_and_b32_e32 v184, 0xffff0000, v200
	v_lshlrev_b32_e32 v185, 16, v201
	v_and_b32_e32 v186, 0xffff0000, v201
	v_lshlrev_b32_e32 v187, 16, v202
	v_and_b32_e32 v198, 0xffff0000, v202
	v_lshlrev_b32_e32 v199, 16, v203
	v_and_b32_e32 v200, 0xffff0000, v203
	v_lshlrev_b32_e32 v201, 16, v204
	v_and_b32_e32 v202, 0xffff0000, v204
	v_lshlrev_b32_e32 v203, 16, v205
	v_and_b32_e32 v204, 0xffff0000, v205
	v_lshlrev_b32_e32 v205, 16, v206
	v_fmac_f32_e32 v205, v108, v161
	v_exp_f32_e32 v161, v175
	v_lshlrev_b32_e32 v211, 16, v208
	v_and_b32_e32 v206, 0xffff0000, v206
	v_and_b32_e32 v208, 0xffff0000, v208
	v_add_f32_e32 v161, 1.0, v161
	v_rcp_f32_e32 v161, v161
	v_lshlrev_b32_e32 v210, 16, v207
	v_lshlrev_b32_e32 v212, 16, v209
	v_and_b32_e32 v207, 0xffff0000, v207
	v_fmac_f32_e32 v211, v104, v161
	v_exp_f32_e32 v104, v172
	v_and_b32_e32 v209, 0xffff0000, v209
	v_add_f32_e32 v108, v205, v187
	v_add_f32_e32 v161, v211, v201
	v_add_f32_e32 v104, 1.0, v104
	v_rcp_f32_e32 v104, v104
	v_lshlrev_b32_e32 v175, 16, v120
	v_and_b32_e32 v120, 0xffff0000, v120
	v_lshlrev_b32_e32 v172, 16, v117
	v_fmac_f32_e32 v206, v109, v104
	v_exp_f32_e32 v109, v184
	v_add_f32_e32 v104, v206, v198
	v_cvt_pk_bf16_f32 v104, v108, v104
	v_and_b32_e32 v117, 0xffff0000, v117
	v_add_f32_e32 v109, 1.0, v109
	v_rcp_f32_e32 v109, v109
	s_nop 0
	v_fmac_f32_e32 v208, v105, v109
	v_exp_f32_e32 v105, v173
	v_add_f32_e32 v109, v208, v202
	v_lshlrev_b32_e32 v173, 16, v118
	v_and_b32_e32 v118, 0xffff0000, v118
	v_add_f32_e32 v105, 1.0, v105
	v_rcp_f32_e32 v105, v105
	s_nop 0
	v_fmac_f32_e32 v210, v110, v105
	v_exp_f32_e32 v110, v185
	v_add_f32_e32 v105, v210, v199
	v_add_f32_e32 v110, 1.0, v110
	v_rcp_f32_e32 v110, v110
	s_nop 0
	v_fmac_f32_e32 v212, v106, v110
	v_exp_f32_e32 v106, v174
	v_add_f32_e32 v110, v212, v203
	v_lshlrev_b32_e32 v174, 16, v119
	v_and_b32_e32 v119, 0xffff0000, v119
	v_add_f32_e32 v106, 1.0, v106
	v_rcp_f32_e32 v106, v106
	s_nop 0
	v_fmac_f32_e32 v207, v111, v106
	v_exp_f32_e32 v111, v186
	v_add_f32_e32 v106, v207, v200
	v_cvt_pk_bf16_f32 v105, v105, v106
	v_cvt_pk_bf16_f32 v106, v161, v109
	v_add_f32_e32 v111, 1.0, v111
	v_rcp_f32_e32 v111, v111
	v_lshl_add_u64 v[108:109], s[6:7], 0, v[182:183]
	v_lshl_add_u64 v[108:109], v[108:109], 0, v[152:153]
	v_lshlrev_b32_e32 v182, 16, v121
	v_fmac_f32_e32 v209, v107, v111
	v_add_f32_e32 v107, v209, v204
	v_cvt_pk_bf16_f32 v107, v110, v107
	global_store_dwordx4 v[108:109], v[104:107], off
	s_nop 1
	v_lshlrev_b32_e32 v110, 16, v124
	v_and_b32_e32 v111, 0xffff0000, v124
	v_lshlrev_b32_e32 v104, 16, v122
	v_exp_f32_e32 v104, v104
	v_and_b32_e32 v105, 0xffff0000, v122
	v_lshlrev_b32_e32 v106, 16, v123
	v_lshlrev_b32_e32 v122, 16, v125
	v_add_f32_e32 v104, 1.0, v104
	v_rcp_f32_e32 v104, v104
	v_and_b32_e32 v107, 0xffff0000, v123
	v_and_b32_e32 v123, 0xffff0000, v125
	v_lshlrev_b32_e32 v124, 16, v114
	v_fmac_f32_e32 v173, v100, v104
	v_exp_f32_e32 v104, v110
	v_and_b32_e32 v114, 0xffff0000, v114
	v_lshlrev_b32_e32 v125, 16, v115
	v_and_b32_e32 v115, 0xffff0000, v115
	v_add_f32_e32 v104, 1.0, v104
	v_rcp_f32_e32 v104, v104
	v_lshlrev_b32_e32 v161, 16, v116
	v_and_b32_e32 v116, 0xffff0000, v116
	v_and_b32_e32 v121, 0xffff0000, v121
	v_fmac_f32_e32 v175, v96, v104
	v_exp_f32_e32 v96, v105
	v_add_f32_e32 v100, v173, v124
	v_add_f32_e32 v104, v175, v161
	v_add_f32_e32 v96, 1.0, v96
	v_rcp_f32_e32 v96, v96
	s_nop 0
	v_fmac_f32_e32 v118, v101, v96
	v_exp_f32_e32 v101, v111
	v_add_f32_e32 v96, v118, v114
	v_cvt_pk_bf16_f32 v96, v100, v96
	v_add_f32_e32 v101, 1.0, v101
	v_rcp_f32_e32 v101, v101
	s_nop 0
	v_fmac_f32_e32 v120, v97, v101
	v_exp_f32_e32 v97, v106
	v_add_f32_e32 v101, v120, v116
	v_add_f32_e32 v97, 1.0, v97
	v_rcp_f32_e32 v97, v97
	s_nop 0
	v_fmac_f32_e32 v174, v102, v97
	v_exp_f32_e32 v102, v122
	v_add_f32_e32 v97, v174, v125
	v_add_f32_e32 v102, 1.0, v102
	v_rcp_f32_e32 v102, v102
	s_nop 0
	v_fmac_f32_e32 v182, v98, v102
	v_exp_f32_e32 v98, v107
	v_add_f32_e32 v102, v182, v172
	v_add_f32_e32 v98, 1.0, v98
	v_rcp_f32_e32 v98, v98
	s_nop 0
	v_fmac_f32_e32 v119, v103, v98
	v_exp_f32_e32 v103, v123
	v_add_f32_e32 v98, v119, v115
	v_cvt_pk_bf16_f32 v97, v97, v98
	v_cvt_pk_bf16_f32 v98, v104, v101
	v_add_f32_e32 v103, 1.0, v103
	v_rcp_f32_e32 v103, v103
	v_lshl_add_u64 v[100:101], s[6:7], 0, v[180:181]
	v_lshl_add_u64 v[110:111], v[100:101], 0, v[152:153]
	v_fmac_f32_e32 v121, v99, v103
	v_add_f32_e32 v99, v121, v117
	v_cvt_pk_bf16_f32 v99, v102, v99
	global_store_dwordx4 v[110:111], v[96:99], off
	s_nop 1
	s_waitcnt vmcnt(2) lgkmcnt(0)
	v_lshlrev_b32_e32 v161, 16, v190
	v_exp_f32_e32 v161, v161
	v_lshlrev_b32_e32 v163, 16, v192
	v_lshlrev_b32_e32 v169, 16, v218
	v_and_b32_e32 v190, 0xffff0000, v190
	v_add_f32_e32 v161, 1.0, v161
	v_rcp_f32_e32 v161, v161
	v_lshlrev_b32_e32 v173, 16, v220
	v_and_b32_e32 v192, 0xffff0000, v192
	v_and_b32_e32 v218, 0xffff0000, v218
	v_fmac_f32_e32 v169, v92, v161
	v_exp_f32_e32 v161, v163
	v_lshlrev_b32_e32 v162, 16, v191
	v_and_b32_e32 v220, 0xffff0000, v220
	v_lshlrev_b32_e32 v164, 16, v193
	v_add_f32_e32 v161, 1.0, v161
	v_rcp_f32_e32 v161, v161
	v_lshlrev_b32_e32 v172, 16, v219
	v_and_b32_e32 v191, 0xffff0000, v191
	v_lshlrev_b32_e32 v174, 16, v221
	v_fmac_f32_e32 v173, v88, v161
	v_exp_f32_e32 v88, v190
	v_and_b32_e32 v193, 0xffff0000, v193
	v_and_b32_e32 v219, 0xffff0000, v219
	v_lshlrev_b32_e32 v165, 16, v214
	v_add_f32_e32 v88, 1.0, v88
	v_rcp_f32_e32 v88, v88
	v_and_b32_e32 v214, 0xffff0000, v214
	v_and_b32_e32 v221, 0xffff0000, v221
	v_lshlrev_b32_e32 v166, 16, v215
	v_fmac_f32_e32 v218, v93, v88
	v_exp_f32_e32 v93, v192
	v_and_b32_e32 v215, 0xffff0000, v215
	v_lshlrev_b32_e32 v168, 16, v217
	v_and_b32_e32 v217, 0xffff0000, v217
	v_add_f32_e32 v93, 1.0, v93
	v_rcp_f32_e32 v93, v93
	v_add_f32_e32 v88, v218, v214
	v_lshlrev_b32_e32 v167, 16, v216
	v_and_b32_e32 v216, 0xffff0000, v216
	v_fmac_f32_e32 v220, v89, v93
	v_exp_f32_e32 v89, v162
	v_add_f32_e32 v92, v169, v165
	v_cvt_pk_bf16_f32 v88, v92, v88
	v_add_f32_e32 v161, v173, v167
	v_add_f32_e32 v89, 1.0, v89
	v_rcp_f32_e32 v89, v89
	v_add_f32_e32 v93, v220, v216
	v_lshlrev_b32_e32 v92, 16, v224
	v_lshlrev_b32_e32 v114, 16, v240
	v_fmac_f32_e32 v172, v94, v89
	v_exp_f32_e32 v94, v164
	v_add_f32_e32 v89, v172, v166
	v_lshlrev_b32_e32 v116, 16, v242
	v_and_b32_e32 v240, 0xffff0000, v240
	v_add_f32_e32 v94, 1.0, v94
	v_rcp_f32_e32 v94, v94
	v_and_b32_e32 v242, 0xffff0000, v242
	v_fmac_f32_e32 v174, v90, v94
	v_exp_f32_e32 v90, v191
	v_add_f32_e32 v94, v174, v168
	v_lshlrev_b32_e32 v115, 16, v241
	v_and_b32_e32 v241, 0xffff0000, v241
	v_add_f32_e32 v90, 1.0, v90
	v_rcp_f32_e32 v90, v90
	s_nop 0
	v_fmac_f32_e32 v219, v95, v90
	v_exp_f32_e32 v95, v193
	v_add_f32_e32 v90, v219, v215
	v_cvt_pk_bf16_f32 v89, v89, v90
	v_cvt_pk_bf16_f32 v90, v161, v93
	v_add_f32_e32 v95, 1.0, v95
	v_rcp_f32_e32 v95, v95
	v_and_b32_e32 v93, 0xffff0000, v224
	v_lshlrev_b32_e32 v117, 16, v243
	v_and_b32_e32 v243, 0xffff0000, v243
	v_fmac_f32_e32 v221, v91, v95
	v_add_f32_e32 v91, v221, v217
	v_cvt_pk_bf16_f32 v91, v94, v91
	global_store_dwordx4 v[126:127], v[88:91], off offset:256
	s_nop 1
	v_lshlrev_b32_e32 v94, 16, v225
	v_and_b32_e32 v95, 0xffff0000, v225
	v_lshlrev_b32_e32 v88, 16, v222
	v_exp_f32_e32 v88, v88
	v_and_b32_e32 v89, 0xffff0000, v222
	v_lshlrev_b32_e32 v90, 16, v223
	v_and_b32_e32 v91, 0xffff0000, v223
	v_add_f32_e32 v88, 1.0, v88
	v_rcp_f32_e32 v88, v88
	v_lshlrev_b32_e32 v100, 16, v236
	v_and_b32_e32 v101, 0xffff0000, v236
	v_lshlrev_b32_e32 v102, 16, v237
	v_fmac_f32_e32 v114, v84, v88
	v_exp_f32_e32 v88, v92
	v_and_b32_e32 v103, 0xffff0000, v237
	v_lshlrev_b32_e32 v104, 16, v238
	v_and_b32_e32 v105, 0xffff0000, v238
	v_add_f32_e32 v88, 1.0, v88
	v_rcp_f32_e32 v88, v88
	v_lshlrev_b32_e32 v106, 16, v239
	v_and_b32_e32 v239, 0xffff0000, v239
	v_add_f32_e32 v84, v114, v100
	v_fmac_f32_e32 v116, v80, v88
	v_exp_f32_e32 v80, v89
	v_add_f32_e32 v88, v116, v104
	v_add_f32_e32 v80, 1.0, v80
	v_rcp_f32_e32 v80, v80
	s_nop 0
	v_fmac_f32_e32 v240, v85, v80
	v_exp_f32_e32 v85, v93
	v_add_f32_e32 v80, v240, v101
	v_cvt_pk_bf16_f32 v80, v84, v80
	v_add_f32_e32 v85, 1.0, v85
	v_rcp_f32_e32 v85, v85
	s_nop 0
	v_fmac_f32_e32 v242, v81, v85
	v_exp_f32_e32 v81, v90
	v_add_f32_e32 v85, v242, v105
	v_add_f32_e32 v81, 1.0, v81
	v_rcp_f32_e32 v81, v81
	s_nop 0
	v_fmac_f32_e32 v115, v86, v81
	v_exp_f32_e32 v86, v94
	v_add_f32_e32 v81, v115, v102
	v_add_f32_e32 v86, 1.0, v86
	v_rcp_f32_e32 v86, v86
	s_nop 0
	v_fmac_f32_e32 v117, v82, v86
	v_exp_f32_e32 v82, v91
	v_add_f32_e32 v86, v117, v106
	v_add_f32_e32 v82, 1.0, v82
	v_rcp_f32_e32 v82, v82
	s_nop 0
	v_fmac_f32_e32 v241, v87, v82
	v_exp_f32_e32 v87, v95
	v_add_f32_e32 v82, v241, v103
	v_cvt_pk_bf16_f32 v81, v81, v82
	v_cvt_pk_bf16_f32 v82, v88, v85
	v_add_f32_e32 v87, 1.0, v87
	v_rcp_f32_e32 v87, v87
	s_nop 0
	v_fmac_f32_e32 v243, v83, v87
	v_add_f32_e32 v83, v243, v239
	v_cvt_pk_bf16_f32 v83, v86, v83
	global_store_dwordx4 v[128:129], v[80:83], off offset:256
	s_nop 1
	global_load_dwordx4 v[92:95], v[130:131], off offset:256
	global_load_dwordx4 v[96:99], v[132:133], off offset:256
	global_load_dwordx4 v[100:103], v[134:135], off offset:256
	global_load_dwordx4 v[88:91], v[136:137], off offset:256
	global_load_dwordx4 v[84:87], v[138:139], off offset:256
	global_load_dwordx4 v[80:83], v[140:141], off offset:256
	s_waitcnt vmcnt(0) lgkmcnt(0)
	v_lshlrev_b32_e32 v104, 16, v92
	v_exp_f32_e32 v104, v104
	v_lshlrev_b32_e32 v106, 16, v94
	v_lshlrev_b32_e32 v118, 16, v100
	v_and_b32_e32 v92, 0xffff0000, v92
	v_add_f32_e32 v104, 1.0, v104
	v_rcp_f32_e32 v104, v104
	v_lshlrev_b32_e32 v120, 16, v102
	v_and_b32_e32 v94, 0xffff0000, v94
	v_and_b32_e32 v100, 0xffff0000, v100
	v_fmac_f32_e32 v118, v76, v104
	v_exp_f32_e32 v104, v106
	v_lshlrev_b32_e32 v105, 16, v93
	v_and_b32_e32 v102, 0xffff0000, v102
	v_lshlrev_b32_e32 v107, 16, v95
	v_add_f32_e32 v104, 1.0, v104
	v_rcp_f32_e32 v104, v104
	v_lshlrev_b32_e32 v119, 16, v101
	v_and_b32_e32 v93, 0xffff0000, v93
	v_lshlrev_b32_e32 v121, 16, v103
	v_fmac_f32_e32 v120, v72, v104
	v_exp_f32_e32 v72, v92
	v_and_b32_e32 v95, 0xffff0000, v95
	v_and_b32_e32 v101, 0xffff0000, v101
	v_lshlrev_b32_e32 v114, 16, v96
	v_add_f32_e32 v72, 1.0, v72
	v_rcp_f32_e32 v72, v72
	v_and_b32_e32 v96, 0xffff0000, v96
	v_and_b32_e32 v103, 0xffff0000, v103
	v_lshlrev_b32_e32 v115, 16, v97
	v_fmac_f32_e32 v100, v77, v72
	v_exp_f32_e32 v77, v94
	v_and_b32_e32 v97, 0xffff0000, v97
	v_lshlrev_b32_e32 v117, 16, v99
	v_and_b32_e32 v99, 0xffff0000, v99
	v_add_f32_e32 v77, 1.0, v77
	v_rcp_f32_e32 v77, v77
	v_add_f32_e32 v72, v100, v96
	v_lshlrev_b32_e32 v116, 16, v98
	v_and_b32_e32 v98, 0xffff0000, v98
	v_fmac_f32_e32 v102, v73, v77
	v_exp_f32_e32 v73, v105
	v_add_f32_e32 v76, v118, v114
	v_cvt_pk_bf16_f32 v72, v76, v72
	v_add_f32_e32 v104, v120, v116
	v_add_f32_e32 v73, 1.0, v73
	v_rcp_f32_e32 v73, v73
	v_add_f32_e32 v77, v102, v98
	v_lshlrev_b32_e32 v76, 16, v90
	v_lshlrev_b32_e32 v92, 16, v80
	v_fmac_f32_e32 v119, v78, v73
	v_exp_f32_e32 v78, v107
	v_add_f32_e32 v73, v119, v115
	v_lshlrev_b32_e32 v94, 16, v82
	v_and_b32_e32 v80, 0xffff0000, v80
	v_add_f32_e32 v78, 1.0, v78
	v_rcp_f32_e32 v78, v78
	v_and_b32_e32 v82, 0xffff0000, v82
	v_fmac_f32_e32 v121, v74, v78
	v_exp_f32_e32 v74, v93
	v_add_f32_e32 v78, v121, v117
	v_lshlrev_b32_e32 v93, 16, v81
	v_and_b32_e32 v81, 0xffff0000, v81
	v_add_f32_e32 v74, 1.0, v74
	v_rcp_f32_e32 v74, v74
	s_nop 0
	v_fmac_f32_e32 v101, v79, v74
	v_exp_f32_e32 v79, v95
	v_add_f32_e32 v74, v101, v97
	v_cvt_pk_bf16_f32 v73, v73, v74
	v_cvt_pk_bf16_f32 v74, v104, v77
	v_add_f32_e32 v79, 1.0, v79
	v_rcp_f32_e32 v79, v79
	v_and_b32_e32 v77, 0xffff0000, v90
	v_lshlrev_b32_e32 v95, 16, v83
	v_and_b32_e32 v83, 0xffff0000, v83
	v_fmac_f32_e32 v103, v75, v79
	v_add_f32_e32 v75, v103, v99
	v_cvt_pk_bf16_f32 v75, v78, v75
	global_store_dwordx4 v[108:109], v[72:75], off offset:256
	s_nop 1
	v_lshlrev_b32_e32 v78, 16, v91
	v_and_b32_e32 v79, 0xffff0000, v91
	v_lshlrev_b32_e32 v72, 16, v88
	v_exp_f32_e32 v72, v72
	v_and_b32_e32 v73, 0xffff0000, v88
	v_lshlrev_b32_e32 v74, 16, v89
	v_and_b32_e32 v75, 0xffff0000, v89
	v_add_f32_e32 v72, 1.0, v72
	v_rcp_f32_e32 v72, v72
	v_lshlrev_b32_e32 v88, 16, v84
	v_and_b32_e32 v84, 0xffff0000, v84
	v_lshlrev_b32_e32 v89, 16, v85
	v_fmac_f32_e32 v92, v68, v72
	v_exp_f32_e32 v72, v76
	v_and_b32_e32 v85, 0xffff0000, v85
	v_lshlrev_b32_e32 v91, 16, v87
	v_and_b32_e32 v87, 0xffff0000, v87
	v_add_f32_e32 v72, 1.0, v72
	v_rcp_f32_e32 v72, v72
	v_lshlrev_b32_e32 v90, 16, v86
	v_and_b32_e32 v86, 0xffff0000, v86
	v_add_f32_e32 v68, v92, v88
	v_fmac_f32_e32 v94, v64, v72
	v_exp_f32_e32 v64, v73
	v_add_f32_e32 v72, v94, v90
	v_add_f32_e32 v64, 1.0, v64
	v_rcp_f32_e32 v64, v64
	s_nop 0
	v_fmac_f32_e32 v80, v69, v64
	v_exp_f32_e32 v69, v77
	v_add_f32_e32 v64, v80, v84
	v_cvt_pk_bf16_f32 v64, v68, v64
	v_add_u32_e32 v68, 0x90, v160
	v_add_f32_e32 v69, 1.0, v69
	v_rcp_f32_e32 v69, v69
	s_nop 0
	v_fmac_f32_e32 v82, v65, v69
	v_exp_f32_e32 v65, v74
	v_add_f32_e32 v69, v82, v86
	v_add_f32_e32 v65, 1.0, v65
	v_rcp_f32_e32 v65, v65
	s_nop 0
	v_fmac_f32_e32 v93, v70, v65
	v_exp_f32_e32 v70, v78
	v_add_f32_e32 v65, v93, v89
	v_add_f32_e32 v70, 1.0, v70
	v_rcp_f32_e32 v70, v70
	s_nop 0
	v_fmac_f32_e32 v95, v66, v70
	v_exp_f32_e32 v66, v75
	v_add_f32_e32 v70, v95, v91
	v_add_f32_e32 v66, 1.0, v66
	v_rcp_f32_e32 v66, v66
	s_nop 0
	v_fmac_f32_e32 v81, v71, v66
	v_exp_f32_e32 v71, v79
	v_add_f32_e32 v66, v81, v85
	v_cvt_pk_bf16_f32 v65, v65, v66
	v_cvt_pk_bf16_f32 v66, v72, v69
	v_add_f32_e32 v71, 1.0, v71
	v_rcp_f32_e32 v71, v71
	v_ashrrev_i32_e32 v69, 31, v68
	v_lshlrev_b64 v[88:89], 11, v[68:69]
	v_lshl_add_u64 v[84:85], v[156:157], 0, v[88:89]
	v_fmac_f32_e32 v83, v67, v71
	v_add_f32_e32 v67, v83, v87
	v_cvt_pk_bf16_f32 v67, v70, v67
	global_store_dwordx4 v[110:111], v[64:67], off offset:256
	s_nop 1
	v_mad_i64_i32 v[82:83], s[0:1], v68, s97, v[158:159]
	s_nop 0
	v_add_u32_e32 v64, 0x80, v160
	v_mad_i64_i32 v[76:77], s[0:1], v64, s97, v[158:159]
	global_load_dwordx4 v[92:95], v[76:77], off
	v_ashrrev_i32_e32 v65, 31, v64
	v_lshlrev_b64 v[90:91], 11, v[64:65]
	v_lshl_add_u64 v[80:81], v[154:155], 0, v[90:91]
	global_load_dwordx4 v[100:103], v[80:81], off
	global_load_dwordx4 v[64:67], v[82:83], off
	v_lshl_add_u64 v[78:79], v[156:157], 0, v[90:91]
	global_load_dwordx4 v[96:99], v[78:79], off
	v_lshl_add_u64 v[86:87], v[154:155], 0, v[88:89]
	global_load_dwordx4 v[68:71], v[84:85], off
	global_load_dwordx4 v[72:75], v[86:87], off
	s_waitcnt vmcnt(0) lgkmcnt(0)
	v_lshlrev_b32_e32 v104, 16, v92
	v_exp_f32_e32 v104, v104
	v_lshlrev_b32_e32 v106, 16, v94
	v_and_b32_e32 v92, 0xffff0000, v92
	v_lshlrev_b32_e32 v114, 16, v100
	v_add_f32_e32 v104, 1.0, v104
	v_rcp_f32_e32 v104, v104
	v_lshlrev_b32_e32 v116, 16, v102
	v_and_b32_e32 v94, 0xffff0000, v94
	v_and_b32_e32 v100, 0xffff0000, v100
	v_fmac_f32_e32 v114, v60, v104
	v_exp_f32_e32 v104, v106
	v_lshlrev_b32_e32 v105, 16, v93
	v_and_b32_e32 v102, 0xffff0000, v102
	v_lshlrev_b32_e32 v107, 16, v95
	v_add_f32_e32 v104, 1.0, v104
	v_rcp_f32_e32 v104, v104
	v_lshlrev_b32_e32 v115, 16, v101
	v_and_b32_e32 v93, 0xffff0000, v93
	v_lshlrev_b32_e32 v117, 16, v103
	v_fmac_f32_e32 v116, v56, v104
	v_exp_f32_e32 v56, v92
	v_and_b32_e32 v95, 0xffff0000, v95
	v_and_b32_e32 v101, 0xffff0000, v101
	v_lshlrev_b32_e32 v108, 16, v96
	v_add_f32_e32 v56, 1.0, v56
	v_rcp_f32_e32 v56, v56
	v_and_b32_e32 v96, 0xffff0000, v96
	v_lshlrev_b32_e32 v109, 16, v97
	v_and_b32_e32 v97, 0xffff0000, v97
	v_fmac_f32_e32 v100, v61, v56
	v_exp_f32_e32 v61, v94
	v_lshlrev_b32_e32 v110, 16, v98
	v_and_b32_e32 v98, 0xffff0000, v98
	v_and_b32_e32 v103, 0xffff0000, v103
	v_add_f32_e32 v61, 1.0, v61
	v_rcp_f32_e32 v61, v61
	v_add_f32_e32 v60, v114, v108
	v_add_f32_e32 v56, v100, v96
	v_lshlrev_b32_e32 v111, 16, v99
	v_fmac_f32_e32 v102, v57, v61
	v_exp_f32_e32 v57, v105
	v_add_f32_e32 v61, v102, v98
	v_and_b32_e32 v99, 0xffff0000, v99
	v_add_f32_e32 v104, v116, v110
	v_add_f32_e32 v57, 1.0, v57
	v_rcp_f32_e32 v57, v57
	v_cvt_pk_bf16_f32 v56, v60, v56
	v_lshlrev_b32_e32 v92, 16, v72
	v_lshlrev_b32_e32 v94, 16, v74
	v_fmac_f32_e32 v115, v62, v57
	v_exp_f32_e32 v62, v107
	v_add_f32_e32 v57, v115, v109
	v_and_b32_e32 v72, 0xffff0000, v72
	v_and_b32_e32 v74, 0xffff0000, v74
	v_add_f32_e32 v62, 1.0, v62
	v_rcp_f32_e32 v62, v62
	s_nop 0
	v_fmac_f32_e32 v117, v58, v62
	v_exp_f32_e32 v58, v93
	v_add_f32_e32 v62, v117, v111
	v_lshlrev_b32_e32 v93, 16, v73
	v_and_b32_e32 v73, 0xffff0000, v73
	v_add_f32_e32 v58, 1.0, v58
	v_rcp_f32_e32 v58, v58
	s_nop 0
	v_fmac_f32_e32 v101, v63, v58
	v_exp_f32_e32 v63, v95
	v_add_f32_e32 v58, v101, v97
	v_cvt_pk_bf16_f32 v57, v57, v58
	v_cvt_pk_bf16_f32 v58, v104, v61
	v_add_f32_e32 v63, 1.0, v63
	v_rcp_f32_e32 v63, v63
	v_lshl_add_u64 v[60:61], s[6:7], 0, v[90:91]
	v_lshl_add_u64 v[60:61], v[60:61], 0, v[152:153]
	v_lshlrev_b32_e32 v95, 16, v75
	v_fmac_f32_e32 v103, v59, v63
	v_add_f32_e32 v59, v103, v99
	v_cvt_pk_bf16_f32 v59, v62, v59
	global_store_dwordx4 v[60:61], v[56:59], off
	s_nop 1
	v_lshlrev_b32_e32 v62, 16, v66
	v_and_b32_e32 v63, 0xffff0000, v66
	v_lshlrev_b32_e32 v56, 16, v64
	v_exp_f32_e32 v56, v56
	v_and_b32_e32 v57, 0xffff0000, v64
	v_lshlrev_b32_e32 v58, 16, v65
	v_lshlrev_b32_e32 v64, 16, v67
	v_add_f32_e32 v56, 1.0, v56
	v_rcp_f32_e32 v56, v56
	v_and_b32_e32 v59, 0xffff0000, v65
	v_and_b32_e32 v65, 0xffff0000, v67
	v_lshlrev_b32_e32 v66, 16, v68
	v_fmac_f32_e32 v92, v52, v56
	v_exp_f32_e32 v56, v62
	v_and_b32_e32 v67, 0xffff0000, v68
	v_lshlrev_b32_e32 v68, 16, v69
	v_and_b32_e32 v69, 0xffff0000, v69
	v_add_f32_e32 v56, 1.0, v56
	v_rcp_f32_e32 v56, v56
	v_lshlrev_b32_e32 v90, 16, v70
	v_and_b32_e32 v70, 0xffff0000, v70
	v_and_b32_e32 v75, 0xffff0000, v75
	v_fmac_f32_e32 v94, v48, v56
	v_exp_f32_e32 v48, v57
	v_add_f32_e32 v52, v92, v66
	v_lshlrev_b32_e32 v91, 16, v71
	v_and_b32_e32 v71, 0xffff0000, v71
	v_add_f32_e32 v48, 1.0, v48
	v_rcp_f32_e32 v48, v48
	v_add_f32_e32 v56, v94, v90
	v_fmac_f32_e32 v72, v53, v48
	v_exp_f32_e32 v53, v63
	v_add_f32_e32 v48, v72, v67
	v_cvt_pk_bf16_f32 v48, v52, v48
	v_add_f32_e32 v53, 1.0, v53
	v_rcp_f32_e32 v53, v53
	s_nop 0
	v_fmac_f32_e32 v74, v49, v53
	v_exp_f32_e32 v49, v58
	v_add_f32_e32 v53, v74, v70
	v_add_f32_e32 v49, 1.0, v49
	v_rcp_f32_e32 v49, v49
	s_nop 0
	v_fmac_f32_e32 v93, v54, v49
	v_exp_f32_e32 v54, v64
	v_add_f32_e32 v49, v93, v68
	v_add_f32_e32 v54, 1.0, v54
	v_rcp_f32_e32 v54, v54
	s_nop 0
	v_fmac_f32_e32 v95, v50, v54
	v_exp_f32_e32 v50, v59
	v_add_f32_e32 v54, v95, v91
	v_add_f32_e32 v50, 1.0, v50
	v_rcp_f32_e32 v50, v50
	s_nop 0
	v_fmac_f32_e32 v73, v55, v50
	v_exp_f32_e32 v55, v65
	v_add_f32_e32 v50, v73, v69
	v_cvt_pk_bf16_f32 v49, v49, v50
	v_cvt_pk_bf16_f32 v50, v56, v53
	v_add_f32_e32 v55, 1.0, v55
	v_rcp_f32_e32 v55, v55
	v_lshl_add_u64 v[52:53], s[6:7], 0, v[88:89]
	v_lshl_add_u64 v[62:63], v[52:53], 0, v[152:153]
	v_fmac_f32_e32 v75, v51, v55
	v_add_f32_e32 v51, v75, v71
	v_cvt_pk_bf16_f32 v51, v54, v51
	global_store_dwordx4 v[62:63], v[48:51], off
	s_nop 1
	v_add_u32_e32 v48, 0xa0, v160
	v_mad_i64_i32 v[64:65], s[0:1], v48, s97, v[158:159]
	global_load_dwordx4 v[92:95], v[64:65], off
	v_ashrrev_i32_e32 v49, 31, v48
	v_lshlrev_b64 v[90:91], 11, v[48:49]
	v_lshl_add_u64 v[68:69], v[154:155], 0, v[90:91]
	global_load_dwordx4 v[100:103], v[68:69], off
	v_lshl_add_u64 v[66:67], v[156:157], 0, v[90:91]
	global_load_dwordx4 v[96:99], v[66:67], off
	v_add_u32_e32 v48, 0xb0, v160
	v_mad_i64_i32 v[70:71], s[0:1], v48, s97, v[158:159]
	global_load_dwordx4 v[56:59], v[70:71], off
	v_ashrrev_i32_e32 v49, 31, v48
	v_lshlrev_b64 v[88:89], 11, v[48:49]
	v_lshl_add_u64 v[72:73], v[156:157], 0, v[88:89]
	v_lshl_add_u64 v[74:75], v[154:155], 0, v[88:89]
	global_load_dwordx4 v[48:51], v[72:73], off
	global_load_dwordx4 v[52:55], v[74:75], off
	s_mov_b64 s[0:1], -1
	s_waitcnt vmcnt(0) lgkmcnt(0)
	global_load_dwordx4 v[122:125], v[76:77], off offset:256
	global_load_dwordx4 v[190:193], v[78:79], off offset:256
	global_load_dwordx4 v[214:217], v[80:81], off offset:256
	global_load_dwordx4 v[218:221], v[82:83], off offset:256
	global_load_dwordx4 v[222:225], v[84:85], off offset:256
	global_load_dwordx4 v[236:239], v[86:87], off offset:256
	v_lshlrev_b32_e32 v104, 16, v92
	v_exp_f32_e32 v104, v104
	v_lshlrev_b32_e32 v106, 16, v94
	v_and_b32_e32 v92, 0xffff0000, v92
	v_lshlrev_b32_e32 v114, 16, v100
	v_add_f32_e32 v104, 1.0, v104
	v_rcp_f32_e32 v104, v104
	v_lshlrev_b32_e32 v116, 16, v102
	v_and_b32_e32 v94, 0xffff0000, v94
	v_and_b32_e32 v100, 0xffff0000, v100
	v_fmac_f32_e32 v114, v44, v104
	v_exp_f32_e32 v104, v106
	v_lshlrev_b32_e32 v105, 16, v93
	v_and_b32_e32 v102, 0xffff0000, v102
	v_lshlrev_b32_e32 v107, 16, v95
	v_add_f32_e32 v104, 1.0, v104
	v_rcp_f32_e32 v104, v104
	v_lshlrev_b32_e32 v115, 16, v101
	v_and_b32_e32 v93, 0xffff0000, v93
	v_lshlrev_b32_e32 v117, 16, v103
	v_fmac_f32_e32 v116, v40, v104
	v_exp_f32_e32 v40, v92
	v_and_b32_e32 v95, 0xffff0000, v95
	v_and_b32_e32 v101, 0xffff0000, v101
	v_lshlrev_b32_e32 v108, 16, v96
	v_add_f32_e32 v40, 1.0, v40
	v_rcp_f32_e32 v40, v40
	v_and_b32_e32 v96, 0xffff0000, v96
	v_lshlrev_b32_e32 v109, 16, v97
	v_and_b32_e32 v97, 0xffff0000, v97
	v_fmac_f32_e32 v100, v45, v40
	v_exp_f32_e32 v45, v94
	v_lshlrev_b32_e32 v110, 16, v98
	v_and_b32_e32 v98, 0xffff0000, v98
	v_and_b32_e32 v103, 0xffff0000, v103
	v_add_f32_e32 v45, 1.0, v45
	v_rcp_f32_e32 v45, v45
	v_lshlrev_b32_e32 v111, 16, v99
	v_and_b32_e32 v99, 0xffff0000, v99
	v_add_f32_e32 v44, v114, v108
	v_fmac_f32_e32 v102, v41, v45
	v_exp_f32_e32 v41, v105
	v_add_f32_e32 v40, v100, v96
	v_add_f32_e32 v45, v102, v98
	v_add_f32_e32 v104, v116, v110
	v_add_f32_e32 v41, 1.0, v41
	v_rcp_f32_e32 v41, v41
	v_cvt_pk_bf16_f32 v40, v44, v40
	v_lshlrev_b32_e32 v92, 16, v52
	v_lshlrev_b32_e32 v94, 16, v54
	v_fmac_f32_e32 v115, v46, v41
	v_exp_f32_e32 v46, v107
	v_add_f32_e32 v41, v115, v109
	v_and_b32_e32 v52, 0xffff0000, v52
	v_and_b32_e32 v54, 0xffff0000, v54
	v_add_f32_e32 v46, 1.0, v46
	v_rcp_f32_e32 v46, v46
	s_nop 0
	v_fmac_f32_e32 v117, v42, v46
	v_exp_f32_e32 v42, v93
	v_add_f32_e32 v46, v117, v111
	v_lshlrev_b32_e32 v93, 16, v53
	v_and_b32_e32 v53, 0xffff0000, v53
	v_add_f32_e32 v42, 1.0, v42
	v_rcp_f32_e32 v42, v42
	s_nop 0
	v_fmac_f32_e32 v101, v47, v42
	v_exp_f32_e32 v47, v95
	v_add_f32_e32 v42, v101, v97
	v_cvt_pk_bf16_f32 v41, v41, v42
	v_cvt_pk_bf16_f32 v42, v104, v45
	v_add_f32_e32 v47, 1.0, v47
	v_rcp_f32_e32 v47, v47
	v_lshl_add_u64 v[44:45], s[6:7], 0, v[90:91]
	v_lshlrev_b32_e32 v95, 16, v55
	v_lshlrev_b32_e32 v90, 16, v50
	v_fmac_f32_e32 v103, v43, v47
	v_add_f32_e32 v43, v103, v99
	v_cvt_pk_bf16_f32 v43, v46, v43
	v_lshl_add_u64 v[46:47], v[44:45], 0, v[152:153]
	global_store_dwordx4 v[46:47], v[40:43], off
	s_nop 1
	v_lshlrev_b32_e32 v44, 16, v58
	v_and_b32_e32 v45, 0xffff0000, v58
	v_lshlrev_b32_e32 v40, 16, v56
	v_exp_f32_e32 v40, v40
	v_and_b32_e32 v41, 0xffff0000, v56
	v_lshlrev_b32_e32 v42, 16, v57
	v_lshlrev_b32_e32 v56, 16, v59
	v_add_f32_e32 v40, 1.0, v40
	v_rcp_f32_e32 v40, v40
	v_and_b32_e32 v43, 0xffff0000, v57
	v_and_b32_e32 v57, 0xffff0000, v59
	v_lshlrev_b32_e32 v58, 16, v48
	v_fmac_f32_e32 v92, v36, v40
	v_exp_f32_e32 v40, v44
	v_and_b32_e32 v48, 0xffff0000, v48
	v_lshlrev_b32_e32 v59, 16, v49
	v_and_b32_e32 v49, 0xffff0000, v49
	v_add_f32_e32 v40, 1.0, v40
	v_rcp_f32_e32 v40, v40
	v_and_b32_e32 v50, 0xffff0000, v50
	v_and_b32_e32 v55, 0xffff0000, v55
	v_add_f32_e32 v36, v92, v58
	v_fmac_f32_e32 v94, v32, v40
	v_exp_f32_e32 v32, v41
	v_lshlrev_b32_e32 v91, 16, v51
	v_and_b32_e32 v51, 0xffff0000, v51
	v_add_f32_e32 v40, v94, v90
	v_add_f32_e32 v32, 1.0, v32
	v_rcp_f32_e32 v32, v32
	s_nop 0
	v_fmac_f32_e32 v52, v37, v32
	v_exp_f32_e32 v37, v45
	v_add_f32_e32 v32, v52, v48
	v_cvt_pk_bf16_f32 v32, v36, v32
	v_add_f32_e32 v37, 1.0, v37
	v_rcp_f32_e32 v37, v37
	s_nop 0
	v_fmac_f32_e32 v54, v33, v37
	v_exp_f32_e32 v33, v42
	v_add_f32_e32 v37, v54, v50
	v_add_f32_e32 v33, 1.0, v33
	v_rcp_f32_e32 v33, v33
	s_nop 0
	v_fmac_f32_e32 v93, v38, v33
	v_exp_f32_e32 v38, v56
	v_add_f32_e32 v33, v93, v59
	v_add_f32_e32 v38, 1.0, v38
	v_rcp_f32_e32 v38, v38
	s_nop 0
	v_fmac_f32_e32 v95, v34, v38
	v_exp_f32_e32 v34, v43
	v_add_f32_e32 v38, v95, v91
	v_add_f32_e32 v34, 1.0, v34
	v_rcp_f32_e32 v34, v34
	s_nop 0
	v_fmac_f32_e32 v53, v39, v34
	v_exp_f32_e32 v39, v57
	v_add_f32_e32 v34, v53, v49
	v_cvt_pk_bf16_f32 v33, v33, v34
	v_cvt_pk_bf16_f32 v34, v40, v37
	v_add_f32_e32 v39, 1.0, v39
	v_rcp_f32_e32 v39, v39
	v_lshl_add_u64 v[36:37], s[6:7], 0, v[88:89]
	v_lshl_add_u64 v[44:45], v[36:37], 0, v[152:153]
	v_fmac_f32_e32 v55, v35, v39
	v_add_f32_e32 v35, v55, v51
	v_cvt_pk_bf16_f32 v35, v38, v35
	global_store_dwordx4 v[44:45], v[32:35], off
	s_nop 1
	s_waitcnt vmcnt(2) lgkmcnt(0)
	v_lshlrev_b32_e32 v76, 16, v122
	v_exp_f32_e32 v76, v76
	v_lshlrev_b32_e32 v78, 16, v124
	v_lshlrev_b32_e32 v84, 16, v214
	v_and_b32_e32 v122, 0xffff0000, v122
	v_add_f32_e32 v76, 1.0, v76
	v_rcp_f32_e32 v76, v76
	v_lshlrev_b32_e32 v86, 16, v216
	v_and_b32_e32 v124, 0xffff0000, v124
	v_and_b32_e32 v214, 0xffff0000, v214
	v_fmac_f32_e32 v84, v28, v76
	v_exp_f32_e32 v76, v78
	v_lshlrev_b32_e32 v77, 16, v123
	v_and_b32_e32 v216, 0xffff0000, v216
	v_lshlrev_b32_e32 v79, 16, v125
	v_add_f32_e32 v76, 1.0, v76
	v_rcp_f32_e32 v76, v76
	v_lshlrev_b32_e32 v85, 16, v215
	v_and_b32_e32 v123, 0xffff0000, v123
	v_lshlrev_b32_e32 v87, 16, v217
	v_fmac_f32_e32 v86, v24, v76
	v_exp_f32_e32 v24, v122
	v_and_b32_e32 v125, 0xffff0000, v125
	v_and_b32_e32 v215, 0xffff0000, v215
	v_lshlrev_b32_e32 v80, 16, v190
	v_add_f32_e32 v24, 1.0, v24
	v_rcp_f32_e32 v24, v24
	v_and_b32_e32 v190, 0xffff0000, v190
	v_and_b32_e32 v217, 0xffff0000, v217
	v_lshlrev_b32_e32 v81, 16, v191
	v_fmac_f32_e32 v214, v29, v24
	v_exp_f32_e32 v29, v124
	v_and_b32_e32 v191, 0xffff0000, v191
	v_lshlrev_b32_e32 v83, 16, v193
	v_and_b32_e32 v193, 0xffff0000, v193
	v_add_f32_e32 v29, 1.0, v29
	v_rcp_f32_e32 v29, v29
	v_add_f32_e32 v24, v214, v190
	v_lshlrev_b32_e32 v82, 16, v192
	v_and_b32_e32 v192, 0xffff0000, v192
	v_fmac_f32_e32 v216, v25, v29
	v_exp_f32_e32 v25, v77
	v_add_f32_e32 v28, v84, v80
	v_cvt_pk_bf16_f32 v24, v28, v24
	v_add_f32_e32 v76, v86, v82
	v_add_f32_e32 v25, 1.0, v25
	v_rcp_f32_e32 v25, v25
	v_add_f32_e32 v29, v216, v192
	v_lshlrev_b32_e32 v28, 16, v220
	v_lshlrev_b32_e32 v48, 16, v236
	v_fmac_f32_e32 v85, v30, v25
	v_exp_f32_e32 v30, v79
	v_add_f32_e32 v25, v85, v81
	v_lshlrev_b32_e32 v50, 16, v238
	v_and_b32_e32 v236, 0xffff0000, v236
	v_add_f32_e32 v30, 1.0, v30
	v_rcp_f32_e32 v30, v30
	v_and_b32_e32 v238, 0xffff0000, v238
	v_fmac_f32_e32 v87, v26, v30
	v_exp_f32_e32 v26, v123
	v_add_f32_e32 v30, v87, v83
	v_lshlrev_b32_e32 v49, 16, v237
	v_and_b32_e32 v237, 0xffff0000, v237
	v_add_f32_e32 v26, 1.0, v26
	v_rcp_f32_e32 v26, v26
	s_nop 0
	v_fmac_f32_e32 v215, v31, v26
	v_exp_f32_e32 v31, v125
	v_add_f32_e32 v26, v215, v191
	v_cvt_pk_bf16_f32 v25, v25, v26
	v_cvt_pk_bf16_f32 v26, v76, v29
	v_add_f32_e32 v31, 1.0, v31
	v_rcp_f32_e32 v31, v31
	v_and_b32_e32 v29, 0xffff0000, v220
	v_lshlrev_b32_e32 v51, 16, v239
	v_and_b32_e32 v239, 0xffff0000, v239
	v_fmac_f32_e32 v217, v27, v31
	v_add_f32_e32 v27, v217, v193
	v_cvt_pk_bf16_f32 v27, v30, v27
	global_store_dwordx4 v[60:61], v[24:27], off offset:256
	s_nop 1
	v_lshlrev_b32_e32 v30, 16, v221
	v_and_b32_e32 v31, 0xffff0000, v221
	v_lshlrev_b32_e32 v24, 16, v218
	v_exp_f32_e32 v24, v24
	v_and_b32_e32 v25, 0xffff0000, v218
	v_lshlrev_b32_e32 v26, 16, v219
	v_and_b32_e32 v27, 0xffff0000, v219
	v_add_f32_e32 v24, 1.0, v24
	v_rcp_f32_e32 v24, v24
	v_lshlrev_b32_e32 v36, 16, v222
	v_and_b32_e32 v37, 0xffff0000, v222
	v_lshlrev_b32_e32 v38, 16, v223
	v_fmac_f32_e32 v48, v20, v24
	v_exp_f32_e32 v24, v28
	v_and_b32_e32 v39, 0xffff0000, v223
	v_lshlrev_b32_e32 v40, 16, v224
	v_and_b32_e32 v41, 0xffff0000, v224
	v_add_f32_e32 v24, 1.0, v24
	v_rcp_f32_e32 v24, v24
	v_lshlrev_b32_e32 v42, 16, v225
	v_and_b32_e32 v225, 0xffff0000, v225
	v_add_f32_e32 v20, v48, v36
	v_fmac_f32_e32 v50, v16, v24
	v_exp_f32_e32 v16, v25
	v_add_f32_e32 v24, v50, v40
	v_add_f32_e32 v16, 1.0, v16
	v_rcp_f32_e32 v16, v16
	s_nop 0
	v_fmac_f32_e32 v236, v21, v16
	v_exp_f32_e32 v21, v29
	v_add_f32_e32 v16, v236, v37
	v_cvt_pk_bf16_f32 v16, v20, v16
	v_add_f32_e32 v21, 1.0, v21
	v_rcp_f32_e32 v21, v21
	s_nop 0
	v_fmac_f32_e32 v238, v17, v21
	v_exp_f32_e32 v17, v26
	v_add_f32_e32 v21, v238, v41
	v_add_f32_e32 v17, 1.0, v17
	v_rcp_f32_e32 v17, v17
	s_nop 0
	v_fmac_f32_e32 v49, v22, v17
	v_exp_f32_e32 v22, v30
	v_add_f32_e32 v17, v49, v38
	v_add_f32_e32 v22, 1.0, v22
	v_rcp_f32_e32 v22, v22
	s_nop 0
	v_fmac_f32_e32 v51, v18, v22
	v_exp_f32_e32 v18, v27
	v_add_f32_e32 v22, v51, v42
	v_add_f32_e32 v18, 1.0, v18
	v_rcp_f32_e32 v18, v18
	s_nop 0
	v_fmac_f32_e32 v237, v23, v18
	v_exp_f32_e32 v23, v31
	v_add_f32_e32 v18, v237, v39
	v_cvt_pk_bf16_f32 v17, v17, v18
	v_cvt_pk_bf16_f32 v18, v24, v21
	v_add_f32_e32 v23, 1.0, v23
	v_rcp_f32_e32 v23, v23
	s_nop 0
	v_fmac_f32_e32 v239, v19, v23
	v_add_f32_e32 v19, v239, v225
	v_cvt_pk_bf16_f32 v19, v22, v19
	global_store_dwordx4 v[62:63], v[16:19], off offset:256
	s_nop 1
	global_load_dwordx4 v[28:31], v[64:65], off offset:256
	global_load_dwordx4 v[32:35], v[66:67], off offset:256
	global_load_dwordx4 v[36:39], v[68:69], off offset:256
	global_load_dwordx4 v[24:27], v[70:71], off offset:256
	global_load_dwordx4 v[20:23], v[72:73], off offset:256
	global_load_dwordx4 v[16:19], v[74:75], off offset:256
	s_waitcnt vmcnt(0) lgkmcnt(0)
	v_lshlrev_b32_e32 v40, 16, v28
	v_exp_f32_e32 v40, v40
	v_lshlrev_b32_e32 v42, 16, v30
	v_lshlrev_b32_e32 v52, 16, v36
	v_and_b32_e32 v28, 0xffff0000, v28
	v_add_f32_e32 v40, 1.0, v40
	v_rcp_f32_e32 v40, v40
	v_lshlrev_b32_e32 v54, 16, v38
	v_and_b32_e32 v30, 0xffff0000, v30
	v_and_b32_e32 v36, 0xffff0000, v36
	v_fmac_f32_e32 v52, v12, v40
	v_exp_f32_e32 v40, v42
	v_lshlrev_b32_e32 v41, 16, v29
	v_and_b32_e32 v38, 0xffff0000, v38
	v_lshlrev_b32_e32 v43, 16, v31
	v_add_f32_e32 v40, 1.0, v40
	v_rcp_f32_e32 v40, v40
	v_lshlrev_b32_e32 v53, 16, v37
	v_and_b32_e32 v29, 0xffff0000, v29
	v_lshlrev_b32_e32 v55, 16, v39
	v_fmac_f32_e32 v54, v8, v40
	v_exp_f32_e32 v8, v28
	v_and_b32_e32 v31, 0xffff0000, v31
	v_and_b32_e32 v37, 0xffff0000, v37
	v_lshlrev_b32_e32 v48, 16, v32
	v_add_f32_e32 v8, 1.0, v8
	v_rcp_f32_e32 v8, v8
	v_and_b32_e32 v32, 0xffff0000, v32
	v_and_b32_e32 v39, 0xffff0000, v39
	v_lshlrev_b32_e32 v49, 16, v33
	v_fmac_f32_e32 v36, v13, v8
	v_exp_f32_e32 v13, v30
	v_and_b32_e32 v33, 0xffff0000, v33
	v_lshlrev_b32_e32 v51, 16, v35
	v_and_b32_e32 v35, 0xffff0000, v35
	v_add_f32_e32 v13, 1.0, v13
	v_rcp_f32_e32 v13, v13
	v_add_f32_e32 v8, v36, v32
	v_lshlrev_b32_e32 v50, 16, v34
	v_and_b32_e32 v34, 0xffff0000, v34
	v_fmac_f32_e32 v38, v9, v13
	v_exp_f32_e32 v9, v41
	v_add_f32_e32 v12, v52, v48
	v_cvt_pk_bf16_f32 v8, v12, v8
	v_add_f32_e32 v40, v54, v50
	v_add_f32_e32 v9, 1.0, v9
	v_rcp_f32_e32 v9, v9
	v_add_f32_e32 v13, v38, v34
	v_lshlrev_b32_e32 v12, 16, v26
	v_lshlrev_b32_e32 v28, 16, v16
	v_fmac_f32_e32 v53, v14, v9
	v_exp_f32_e32 v14, v43
	v_add_f32_e32 v9, v53, v49
	v_lshlrev_b32_e32 v30, 16, v18
	v_and_b32_e32 v16, 0xffff0000, v16
	v_add_f32_e32 v14, 1.0, v14
	v_rcp_f32_e32 v14, v14
	v_and_b32_e32 v18, 0xffff0000, v18
	v_fmac_f32_e32 v55, v10, v14
	v_exp_f32_e32 v10, v29
	v_add_f32_e32 v14, v55, v51
	v_lshlrev_b32_e32 v29, 16, v17
	v_and_b32_e32 v17, 0xffff0000, v17
	v_add_f32_e32 v10, 1.0, v10
	v_rcp_f32_e32 v10, v10
	s_nop 0
	v_fmac_f32_e32 v37, v15, v10
	v_exp_f32_e32 v15, v31
	v_add_f32_e32 v10, v37, v33
	v_cvt_pk_bf16_f32 v9, v9, v10
	v_cvt_pk_bf16_f32 v10, v40, v13
	v_add_f32_e32 v15, 1.0, v15
	v_rcp_f32_e32 v15, v15
	v_and_b32_e32 v13, 0xffff0000, v26
	v_lshlrev_b32_e32 v31, 16, v19
	v_and_b32_e32 v19, 0xffff0000, v19
	v_fmac_f32_e32 v39, v11, v15
	v_add_f32_e32 v11, v39, v35
	v_cvt_pk_bf16_f32 v11, v14, v11
	global_store_dwordx4 v[46:47], v[8:11], off offset:256
	s_nop 1
	v_lshlrev_b32_e32 v14, 16, v27
	v_and_b32_e32 v15, 0xffff0000, v27
	v_lshlrev_b32_e32 v8, 16, v24
	v_exp_f32_e32 v8, v8
	v_and_b32_e32 v9, 0xffff0000, v24
	v_lshlrev_b32_e32 v10, 16, v25
	v_and_b32_e32 v11, 0xffff0000, v25
	v_add_f32_e32 v8, 1.0, v8
	v_rcp_f32_e32 v8, v8
	v_lshlrev_b32_e32 v24, 16, v20
	v_and_b32_e32 v20, 0xffff0000, v20
	v_lshlrev_b32_e32 v25, 16, v21
	v_fmac_f32_e32 v28, v4, v8
	v_exp_f32_e32 v8, v12
	v_and_b32_e32 v21, 0xffff0000, v21
	v_lshlrev_b32_e32 v27, 16, v23
	v_and_b32_e32 v23, 0xffff0000, v23
	v_add_f32_e32 v8, 1.0, v8
	v_rcp_f32_e32 v8, v8
	v_lshlrev_b32_e32 v26, 16, v22
	v_and_b32_e32 v22, 0xffff0000, v22
	v_add_f32_e32 v4, v28, v24
	v_fmac_f32_e32 v30, v0, v8
	v_exp_f32_e32 v0, v9
	v_add_f32_e32 v8, v30, v26
	v_add_f32_e32 v0, 1.0, v0
	v_rcp_f32_e32 v0, v0
	s_nop 0
	v_fmac_f32_e32 v16, v5, v0
	v_exp_f32_e32 v5, v13
	v_add_f32_e32 v0, v16, v20
	v_cvt_pk_bf16_f32 v0, v4, v0
	v_add_f32_e32 v5, 1.0, v5
	v_rcp_f32_e32 v5, v5
	s_nop 0
	v_fmac_f32_e32 v18, v1, v5
	v_exp_f32_e32 v1, v10
	v_add_f32_e32 v5, v18, v22
	v_add_f32_e32 v1, 1.0, v1
	v_rcp_f32_e32 v1, v1
	s_nop 0
	v_fmac_f32_e32 v29, v6, v1
	v_exp_f32_e32 v6, v14
	v_add_f32_e32 v1, v29, v25
	v_add_f32_e32 v6, 1.0, v6
	v_rcp_f32_e32 v6, v6
	s_nop 0
	v_fmac_f32_e32 v31, v2, v6
	v_exp_f32_e32 v2, v11
	v_add_f32_e32 v6, v31, v27
	v_add_f32_e32 v2, 1.0, v2
	v_rcp_f32_e32 v2, v2
	s_nop 0
	v_fmac_f32_e32 v17, v7, v2
	v_exp_f32_e32 v7, v15
	v_add_f32_e32 v2, v17, v21
	v_cvt_pk_bf16_f32 v1, v1, v2
	v_cvt_pk_bf16_f32 v2, v8, v5
	v_add_f32_e32 v7, 1.0, v7
	v_rcp_f32_e32 v7, v7
	s_nop 0
	v_fmac_f32_e32 v19, v3, v7
	v_add_f32_e32 v3, v19, v23
	v_cvt_pk_bf16_f32 v3, v6, v3
	global_store_dwordx4 v[44:45], v[0:3], off offset:256
	s_nop 1
	s_cbranch_vccnz .LBB0_793
	s_andn2_b64 vcc, exec, s[4:5]
	s_cbranch_vccnz .LBB0_792
	s_barrier
	s_branch .LBB0_792
